# V^T transpose loop: next tile's global load issued before the closing barrier of the current tile
# speedup vs baseline: 1.0093x; 1.0093x over previous
.LBB0_327:
	s_mov_b64 s[4:5], 0x8b89000
	v_lshl_add_u64 v[18:19], v[46:47], 0, s[4:5]
	v_readlane_b32 s4, v254, 6
	v_readlane_b32 s5, v254, 7
	v_lshl_add_u32 v8, s18, 6, v136
	s_andn2_b64 vcc, exec, s[4:5]
	s_waitcnt lgkmcnt(0)
	s_barrier
	s_cbranch_vccnz .LBB0_330
	v_ashrrev_i32_e32 v7, 3, v8
	v_lshlrev_b32_e32 v5, 2, v7
	s_mov_b64 s[4:5], 0x6b89000
	v_lshlrev_b32_e32 v6, 3, v136
	v_lshlrev_b32_e32 v4, 1, v7
	v_and_b32_e32 v5, 16, v5
	v_lshl_add_u64 v[2:3], v[46:47], 0, s[4:5]
	v_and_b32_e32 v0, 56, v6
	v_add_u32_e32 v5, 0, v5
	v_and_b32_e32 v4, 0xffffffe6, v4
	v_and_b32_e32 v9, 8, v7
	s_movk_i32 s4, 0x90
	v_add3_u32 v12, v5, v4, v9
	v_mul_lo_u32 v4, v7, s4
	v_lshlrev_b32_e32 v5, 1, v0
	v_add3_u32 v9, 0, v4, v5
	v_bfe_u32 v11, v6, 4, 2
	v_lshlrev_b32_e32 v4, 4, v7
	v_and_b32_e32 v6, 8, v6
	v_mul_u32_u24_e32 v13, 0x90, v0
	v_readlane_b32 s4, v254, 53
	v_readlane_b32 s5, v254, 10
	v_ashrrev_i32_e32 v5, 31, v4
	v_add_u32_e32 v10, s4, v7
	s_lshl_b32 s4, s42, 6
	v_add_u32_e32 v11, s5, v11
	s_lshl_b32 s5, s42, 2
	v_lshlrev_b32_e32 v0, 1, v0
	v_add_u32_e32 v12, v12, v13
	v_lshlrev_b32_e32 v6, 1, v6
	s_mov_b32 s6, s2
	s_ashr_i32 s7, s6, 31
	s_lshr_b32 s8, s7, 23
	s_lshr_b32 s7, s7, 26
	s_add_i32 s8, s6, s8
	s_add_i32 s7, s6, s7
	s_ashr_i32 s14, s8, 9
	s_ashr_i32 s7, s7, 6
	s_lshr_b32 s8, s7, 29
	s_lshl_b32 s9, s14, 7
	s_lshl_b32 s10, s14, 6
	s_add_i32 s8, s7, s8
	s_and_b32 s9, s9, 0xffffff00
	s_and_b32 s10, s10, 64
	s_and_b32 s8, s8, -8
	s_or_b32 s9, s9, s10
	s_sub_i32 s8, s7, s8
	s_addk_i32 s9, 0x380
	s_cmpk_lt_i32 s6, 0x800
	s_cselect_b32 s10, s9, 0x740
	s_ashr_i32 s9, s8, 31
	s_lshl_b64 s[12:13], s[8:9], 12
	s_lshl_b32 s9, s7, 12
	v_subrev_u32_e32 v14, s9, v10
	v_ashrrev_i32_e32 v15, 31, v14
	v_lshl_add_u64 v[14:15], s[12:13], 0, v[14:15]
	v_mad_u64_u32 v[16:17], s[12:13], v14, s61, v[18:19]
	s_ashr_i32 s11, s10, 31
	v_mad_i32_i24 v17, v15, s61, v17
	v_lshl_add_u64 v[14:15], s[10:11], 1, v[16:17]
	v_lshl_add_u64 v[14:15], v[14:15], 0, v[0:1]
	global_load_dwordx4 v[14:17], v[14:15], off
.LBB0_329:
	s_lshl_b32 s9, s14, 3
	s_add_i32 s8, s9, s8
	s_lshl_b32 s7, s7, 8
	s_ashr_i32 s9, s8, 31
	v_subrev_u32_e32 v22, s7, v11
	s_lshl_b64 s[8:9], s[8:9], 19
	v_ashrrev_i32_e32 v23, 31, v22
	v_lshl_add_u64 v[20:21], v[2:3], 0, s[8:9]
	v_lshlrev_b64 v[22:23], 11, v[22:23]
	v_lshl_add_u64 v[20:21], v[20:21], 0, v[22:23]
	v_lshl_add_u64 v[20:21], v[4:5], 1, v[20:21]
	v_mov_b32_e32 v7, v1
	s_add_i32 s6, s6, s42
	v_lshl_add_u64 v[20:21], v[20:21], 0, v[6:7]
	v_add_u32_e32 v10, s4, v10
	v_add_u32_e32 v11, s5, v11
	s_cmpk_gt_i32 s6, 0x9ff
	s_waitcnt vmcnt(0) lgkmcnt(0)
	ds_write_b16 v12, v14
	ds_write_b16_d16_hi v12, v14 offset:144
	ds_write_b16 v12, v15 offset:288
	ds_write_b16_d16_hi v12, v15 offset:432
	ds_write_b16 v12, v16 offset:576
	ds_write_b16_d16_hi v12, v16 offset:720
	ds_write_b16 v12, v17 offset:864
	ds_write_b16_d16_hi v12, v17 offset:1008
	s_waitcnt lgkmcnt(0)
	s_barrier
	ds_read_b128 v[14:17], v9
	s_waitcnt lgkmcnt(0)
	global_store_dwordx4 v[20:21], v[14:17], off
	s_cmpk_gt_i32 s6, 0x9ff
	s_cbranch_scc1 .Lvt_nopf
	s_ashr_i32 s7, s6, 31
	s_lshr_b32 s8, s7, 23
	s_lshr_b32 s7, s7, 26
	s_add_i32 s8, s6, s8
	s_add_i32 s7, s6, s7
	s_ashr_i32 s14, s8, 9
	s_ashr_i32 s7, s7, 6
	s_lshr_b32 s8, s7, 29
	s_lshl_b32 s9, s14, 7
	s_lshl_b32 s10, s14, 6
	s_add_i32 s8, s7, s8
	s_and_b32 s9, s9, 0xffffff00
	s_and_b32 s10, s10, 64
	s_and_b32 s8, s8, -8
	s_or_b32 s9, s9, s10
	s_sub_i32 s8, s7, s8
	s_addk_i32 s9, 0x380
	s_cmpk_lt_i32 s6, 0x800
	s_cselect_b32 s10, s9, 0x740
	s_ashr_i32 s9, s8, 31
	s_lshl_b64 s[12:13], s[8:9], 12
	s_lshl_b32 s9, s7, 12
	v_subrev_u32_e32 v14, s9, v10
	v_ashrrev_i32_e32 v15, 31, v14
	v_lshl_add_u64 v[14:15], s[12:13], 0, v[14:15]
	v_mad_u64_u32 v[16:17], s[12:13], v14, s61, v[18:19]
	s_ashr_i32 s11, s10, 31
	v_mad_i32_i24 v17, v15, s61, v17
	v_lshl_add_u64 v[14:15], s[10:11], 1, v[16:17]
	v_lshl_add_u64 v[14:15], v[14:15], 0, v[0:1]
	global_load_dwordx4 v[14:17], v[14:15], off
.Lvt_nopf:
	s_waitcnt lgkmcnt(0)
	s_barrier
	s_cmpk_gt_i32 s6, 0x9ff
	s_cbranch_scc0 .LBB0_329
